# v65 + down-GEMM tile order: each XCD takes 4 row panels x 8 column tiles per round instead of 2 x 16 (12 instead of 18 operand panels per XCD, every A panel still consumed within one round); bit-ident
# speedup vs baseline: 1.0119x; 1.0040x over previous
.LBB0_1985:
	s_and_b64 vcc, exec, s[2:3]
	s_cbranch_vccz .LBB0_2019
	s_and_b32 s41, s36, 6
	s_lshl_b32 s41, s41, 1
	s_ashr_i32 s2, s36, 6
	s_add_i32 s41, s41, s2
	s_and_b32 s42, s36, 1
	s_lshl_b32 s42, s42, 3
	s_bfe_u32 s2, s36, 0x30003
	s_add_i32 s42, s42, s2
	s_mul_i32 s23, s42, 0x560000
	s_add_u32 s4, s37, s23
	s_addc_u32 s5, s40, 0
	s_add_u32 s6, s4, 0x2b0000
	s_mul_i32 s3, s41, 0x560000
	s_addc_u32 s7, s5, 0
	s_mul_hi_i32 s2, s41, 0x560000
	s_add_u32 s28, s38, s3
	s_addc_u32 s29, s39, s2
	s_add_u32 s2, s28, 0x2b0000
	s_getreg_b32 s16, hwreg(HW_REG_HW_ID, 0, 6)
	s_addc_u32 s3, s29, 0
	s_lshl_b32 s16, s16, 2
	s_and_b32 s16, s16, 0xfc
	s_add_i32 s16, s16, 0
	s_add_i32 s16, s16, 0x20200
	v_mov_b32_e32 v0, s16
	ds_read_b32 v0, v0
	s_movk_i32 s24, 0x2b00
	v_mov_b32_e32 v133, 0
	v_mov_b32_e32 v129, v133
	v_mov_b32_e32 v135, v133
	s_waitcnt lgkmcnt(0)
	v_readfirstlane_b32 s16, v0
	v_mbcnt_lo_u32_b32 v0, -1, 0
	v_mbcnt_hi_u32_b32 v0, -1, v0
	v_mov_b32_e32 v131, v133
	s_nop 0
	v_lshl_add_u32 v9, s16, 6, v0
	s_mov_b32 s16, 0xffffe0
	v_lshlrev_b32_e32 v0, 4, v9
	v_add_u32_e32 v1, 0x2000, v0
	v_ashrrev_i32_e32 v2, 31, v1
	v_lshrrev_b32_e32 v2, 22, v2
	v_add_u32_e32 v2, v1, v2
	v_ashrrev_i32_e32 v8, 10, v2
	v_mul_i32_i24_e32 v2, 0x400, v8
	v_sub_u32_e32 v1, v1, v2
	v_lshrrev_b32_e32 v2, 4, v1
	v_bitop3_b32 v1, v2, v1, 32 bitop3:0x6c
	v_ashrrev_i32_e32 v2, 31, v1
	v_lshrrev_b32_e32 v2, 26, v2
	v_add_u32_e32 v2, v1, v2
	v_lshlrev_b32_e32 v3, 3, v8
	v_ashrrev_i32_e32 v10, 6, v2
	v_and_b32_e32 v3, -16, v3
	v_add_u32_e32 v3, v10, v3
	v_and_b32_e32 v4, 3, v10
	v_lshrrev_b32_e32 v5, 2, v3
	v_lshlrev_b32_e32 v6, 1, v3
	v_and_b32_e32 v2, 0xc0, v2
	v_and_or_b32 v4, v3, s16, v4
	v_and_b32_e32 v5, 4, v5
	v_and_b32_e32 v6, 24, v6
	v_sub_u32_e32 v1, v1, v2
	v_mov_b32_e32 v2, 1
	v_or3_b32 v4, v4, v5, v6
	v_lshlrev_b32_e32 v5, 5, v8
	v_ashrrev_i16_sdwa v1, v2, sext(v1) dst_sel:DWORD dst_unused:UNUSED_PAD src0_sel:DWORD src1_sel:BYTE_0
	v_and_b32_e32 v11, 32, v5
	v_bfe_i32 v12, v1, 0, 16
	v_mul_u32_u24_e32 v4, 0x2b00, v4
	v_add_u32_e32 v1, v11, v12
	v_mul_lo_u32 v3, v3, s24
	v_add_lshl_u32 v128, v4, v1, 1
	v_add_lshl_u32 v130, v1, v3, 1
	v_bfe_i32 v1, v9, 27, 1
	v_lshrrev_b32_e32 v1, 22, v1
	v_add_u32_e32 v1, v0, v1
	v_and_b32_e32 v1, 0xfffffc00, v1
	v_sub_u32_e32 v0, v0, v1
	v_lshrrev_b32_e32 v1, 4, v0
	v_ashrrev_i32_e32 v3, 31, v9
	v_bitop3_b32 v0, v1, v0, 32 bitop3:0x6c
	v_lshrrev_b32_e32 v3, 26, v3
	v_ashrrev_i32_e32 v1, 31, v0
	v_add_u32_e32 v3, v9, v3
	v_lshrrev_b32_e32 v1, 26, v1
	v_ashrrev_i32_e32 v14, 6, v3
	v_add_u32_e32 v1, v0, v1
	v_lshlrev_b32_e32 v3, 3, v14
	v_ashrrev_i32_e32 v13, 6, v1
	v_and_b32_e32 v3, -16, v3
	v_add_u32_e32 v3, v13, v3
	v_and_b32_e32 v4, 3, v13
	v_lshrrev_b32_e32 v5, 2, v3
	v_lshlrev_b32_e32 v6, 1, v3
	v_and_b32_e32 v1, 0xc0, v1
	v_readfirstlane_b32 s20, v9
	v_and_or_b32 v4, v3, s16, v4
	v_and_b32_e32 v5, 4, v5
	v_and_b32_e32 v6, 24, v6
	v_sub_u32_e32 v0, v0, v1
	s_ashr_i32 s21, s20, 6
	v_or3_b32 v4, v4, v5, v6
	v_lshlrev_b32_e32 v5, 5, v14
	v_ashrrev_i16_sdwa v0, v2, sext(v0) dst_sel:DWORD dst_unused:UNUSED_PAD src0_sel:DWORD src1_sel:BYTE_0
	s_lshl_b32 s22, s21, 10
	v_and_b32_e32 v15, 32, v5
	v_bfe_i32 v16, v0, 0, 16
	v_mul_u32_u24_e32 v4, 0x2b00, v4
	v_add_u32_e32 v0, v15, v16
	s_add_i32 s40, s22, 0
	v_add_lshl_u32 v132, v4, v0, 1
	s_add_i32 m0, s40, 0x10000
	v_mul_lo_u32 v1, v3, s24
	global_load_lds_dwordx4 v132, s[4:5]
	s_add_i32 m0, s40, 0x12000
	v_add_lshl_u32 v134, v0, v1, 1
	global_load_lds_dwordx4 v128, s[4:5]
	s_add_i32 m0, s40, 0x14000
	s_add_i32 s43, s40, 0x2000
	global_load_lds_dwordx4 v132, s[6:7]
	s_add_i32 m0, s40, 0x16000
	s_add_i32 s44, s40, 0x4000
	global_load_lds_dwordx4 v128, s[6:7]
	s_mov_b32 m0, s40
	s_add_i32 s45, s40, 0x6000
	global_load_lds_dwordx4 v134, s[28:29]
	s_mov_b32 m0, s43
	s_mov_b32 s7, 0
	global_load_lds_dwordx4 v130, s[28:29]
	s_mov_b32 m0, s44
	v_lshl_add_u64 v[6:7], s[4:5], 0, v[132:133]
	global_load_lds_dwordx4 v134, s[2:3]
	s_mov_b32 m0, s45
	v_lshl_add_u64 v[4:5], s[4:5], 0, v[128:129]
	global_load_lds_dwordx4 v130, s[2:3]
	s_ashr_i32 s2, s20, 8
	s_cmp_eq_u32 s2, 1
	v_lshl_add_u64 v[0:1], s[28:29], 0, v[134:135]
	s_cselect_b64 s[16:17], -1, 0
	s_cmp_lg_u32 s2, 1
	v_lshl_add_u64 v[2:3], s[28:29], 0, v[130:131]
	s_cbranch_scc1 .LBB0_1988
	s_barrier
